# conv transposed path: batched the 8 per-step LDS element reads ahead of their consumers
# baseline (speedup 1.0000x reference)
; __device__ __forceinline__ unsigned pk2(float lo, float hi) { const f32x2 v = {lo, hi}; const bf16x2_t b = __builtin_convertvector(v, bf16x2_t); return __builtin_bit_cast(unsigned, b); }
; __device__ __forceinline__ float silu(float x) { return x * __builtin_amdgcn_rcpf(1.f + __builtin_amdgcn_exp2f(-1.4426950408889634f * x)); }
; __device__ __forceinline__ void ph_conv(LAS unsigned char* lds) {
;     ...
;             for (int q = 0; q < 16; ++q) {
;                 float uu[11]; uu[0] = u0; uu[1] = u1; uu[2] = u2;
; #pragma unroll
;                 for (int i = 0; i < 8; ++i) uu[3 + i] = bf2f_lds(tp + (q * 8 + 3 + i) * 128);
;                 float ov[8];
; #pragma unroll
;                 for (int j = 0; j < 8; ++j) ov[j] = silu(bb + w0 * uu[j] + w1 * uu[j + 1] + w2 * uu[j + 2] + w3 * uu[j + 3]);
;                 u32x4 w; w.x = pk2(ov[0], ov[1]); w.y = pk2(ov[2], ov[3]); w.z = pk2(ov[4], ov[5]); w.w = pk2(ov[6], ov[7]);
;                 *(u32x4*)(dst + (unsigned)(ch * 128 + q * 8)) = w;
;                 u0 = uu[8]; u1 = uu[9]; u2 = uu[10];
;             }
.LBB0_735:
	v_add_u32_e32 v0, s10, v83
	ds_read_u16 v144, v0
	ds_read_u16 v145, v0 offset:768
	ds_read_u16 v146, v0 offset:640
	ds_read_u16 v147, v0 offset:896
	ds_read_u16 v148, v0 offset:384
	ds_read_u16 v149, v0 offset:512
	ds_read_u16 v150, v0 offset:128
	ds_read_u16 v151, v0 offset:256
	v_pk_fma_f32 v[28:29], v[2:3], v[16:17], v[4:5]
	s_addk_i32 s10, 0x800
	s_cmpk_lg_i32 s10, 0x4000
	s_waitcnt lgkmcnt(0)
	ds_read_u16 v152, v0 offset:1024
	ds_read_u16 v153, v0 offset:1792
	ds_read_u16 v154, v0 offset:1664
	ds_read_u16 v155, v0 offset:1920
	ds_read_u16 v156, v0 offset:1408
	ds_read_u16 v157, v0 offset:1536
	ds_read_u16 v158, v0 offset:1152
	ds_read_u16 v159, v0 offset:1280
	v_lshlrev_b32_e32 v19, 16, v144
	v_lshlrev_b32_e32 v21, 16, v145
	v_lshlrev_b32_e32 v20, 16, v146
	v_lshlrev_b32_e32 v23, 16, v147
	v_lshlrev_b32_e32 v24, 16, v148
	v_lshlrev_b32_e32 v25, 16, v149
	v_lshlrev_b32_e32 v26, 16, v150
	v_mov_b32_e32 v14, v17
	v_lshlrev_b32_e32 v27, 16, v151
	v_pk_fma_f32 v[16:17], v[6:7], v[14:15], v[28:29]
	v_mov_b32_e32 v18, v15
	v_pk_fma_f32 v[14:15], v[8:9], v[18:19], v[16:17]
	v_mov_b32_e32 v16, v19
	v_mov_b32_e32 v17, v26
	v_pk_fma_f32 v[14:15], v[10:11], v[16:17], v[14:15]
	v_pk_fma_f32 v[18:19], v[2:3], v[18:19], v[4:5]
	v_mul_f32_e32 v22, 0xbfb8aa3b, v14
	v_exp_f32_e32 v22, v22
	v_pk_fma_f32 v[16:17], v[6:7], v[16:17], v[18:19]
	v_pk_mov_b32 v[30:31], v[26:27], v[24:25] op_sel:[1,0]
	v_pk_fma_f32 v[16:17], v[8:9], v[26:27], v[16:17]
	v_add_f32_e32 v22, 1.0, v22
	v_rcp_f32_e32 v28, v22
	v_mul_f32_e32 v22, 0xbfb8aa3b, v15
	v_exp_f32_e32 v22, v22
	v_pk_fma_f32 v[16:17], v[10:11], v[30:31], v[16:17]
	v_add_f32_e32 v22, 1.0, v22
	v_mul_f32_e32 v18, 0xbfb8aa3b, v16
	v_mul_f32_e32 v19, 0xbfb8aa3b, v17
	v_exp_f32_e32 v18, v18
	v_exp_f32_e32 v19, v19
	v_rcp_f32_e32 v29, v22
	v_add_f32_e32 v18, 1.0, v18
	v_add_f32_e32 v19, 1.0, v19
	v_rcp_f32_e32 v18, v18
	v_rcp_f32_e32 v19, v19
	v_pk_mul_f32 v[14:15], v[14:15], v[28:29]
	v_pk_fma_f32 v[28:29], v[2:3], v[26:27], v[4:5]
	v_cvt_pk_bf16_f32 v14, v14, v15
	v_pk_fma_f32 v[26:27], v[6:7], v[30:31], v[28:29]
	v_pk_mul_f32 v[16:17], v[16:17], v[18:19]
	v_pk_mov_b32 v[18:19], v[24:25], v[20:21] op_sel:[1,0]
	v_pk_fma_f32 v[26:27], v[8:9], v[24:25], v[26:27]
	v_pk_fma_f32 v[24:25], v[2:3], v[24:25], v[4:5]
	v_pk_fma_f32 v[26:27], v[10:11], v[18:19], v[26:27]
	v_pk_fma_f32 v[18:19], v[6:7], v[18:19], v[24:25]
	v_mul_f32_e32 v22, 0xbfb8aa3b, v26
	v_exp_f32_e32 v22, v22
	v_pk_fma_f32 v[18:19], v[8:9], v[20:21], v[18:19]
	v_cvt_pk_bf16_f32 v15, v16, v17
	v_add_f32_e32 v22, 1.0, v22
	v_rcp_f32_e32 v28, v22
	v_mul_f32_e32 v22, 0xbfb8aa3b, v27
	v_exp_f32_e32 v22, v22
	s_nop 0
	v_add_f32_e32 v22, 1.0, v22
	v_rcp_f32_e32 v29, v22
	v_mov_b32_e32 v22, v21
	v_pk_fma_f32 v[18:19], v[10:11], v[22:23], v[18:19]
	v_pk_fma_f32 v[20:21], v[2:3], v[20:21], v[4:5]
	v_mul_f32_e32 v24, 0xbfb8aa3b, v18
	v_mul_f32_e32 v25, 0xbfb8aa3b, v19
	v_exp_f32_e32 v24, v24
	v_exp_f32_e32 v25, v25
	v_pk_mul_f32 v[26:27], v[26:27], v[28:29]
	v_pk_fma_f32 v[20:21], v[6:7], v[22:23], v[20:21]
	v_add_f32_e32 v24, 1.0, v24
	v_add_f32_e32 v25, 1.0, v25
	v_rcp_f32_e32 v24, v24
	v_rcp_f32_e32 v25, v25
	v_cvt_pk_bf16_f32 v16, v26, v27
	v_pk_mul_f32 v[18:19], v[18:19], v[24:25]
	s_nop 0
	v_cvt_pk_bf16_f32 v17, v18, v19
	global_store_dwordx4 v[12:13], v[14:17], off offset:-16
	s_waitcnt lgkmcnt(0)
	v_lshlrev_b32_e32 v19, 16, v152
	v_mov_b32_e32 v22, v19
	v_lshlrev_b32_e32 v17, 16, v153
	v_lshlrev_b32_e32 v16, 16, v154
	v_lshlrev_b32_e32 v15, 16, v155
	v_lshlrev_b32_e32 v24, 16, v156
	v_lshlrev_b32_e32 v25, 16, v157
	v_mov_b32_e32 v18, v23
	v_pk_fma_f32 v[20:21], v[8:9], v[18:19], v[20:21]
	v_lshlrev_b32_e32 v26, 16, v158
	v_mov_b32_e32 v23, v26
	v_pk_fma_f32 v[20:21], v[10:11], v[22:23], v[20:21]
	v_lshlrev_b32_e32 v27, 16, v159
	v_mul_f32_e32 v0, 0xbfb8aa3b, v20
	v_exp_f32_e32 v0, v0
	v_pk_fma_f32 v[18:19], v[2:3], v[18:19], v[4:5]
	v_pk_mov_b32 v[30:31], v[26:27], v[24:25] op_sel:[1,0]
	v_pk_fma_f32 v[18:19], v[6:7], v[22:23], v[18:19]
	v_add_f32_e32 v0, 1.0, v0
	v_rcp_f32_e32 v28, v0
	v_mul_f32_e32 v0, 0xbfb8aa3b, v21
	v_exp_f32_e32 v0, v0
	v_pk_fma_f32 v[18:19], v[8:9], v[26:27], v[18:19]
	v_mov_b32_e32 v14, v17
	v_pk_fma_f32 v[18:19], v[10:11], v[30:31], v[18:19]
	v_add_f32_e32 v0, 1.0, v0
	v_rcp_f32_e32 v29, v0
	v_mul_f32_e32 v0, 0xbfb8aa3b, v18
	v_exp_f32_e32 v0, v0
	v_pk_mul_f32 v[20:21], v[20:21], v[28:29]
	v_pk_fma_f32 v[28:29], v[2:3], v[26:27], v[4:5]
	v_add_f32_e32 v0, 1.0, v0
	v_rcp_f32_e32 v22, v0
	v_mul_f32_e32 v0, 0xbfb8aa3b, v19
	v_exp_f32_e32 v0, v0
	v_pk_fma_f32 v[26:27], v[6:7], v[30:31], v[28:29]
	v_add_f32_e32 v0, 1.0, v0
	v_rcp_f32_e32 v23, v0
	v_pk_fma_f32 v[26:27], v[8:9], v[24:25], v[26:27]
	v_pk_mul_f32 v[22:23], v[18:19], v[22:23]
	v_pk_mov_b32 v[18:19], v[24:25], v[16:17] op_sel:[1,0]
	v_pk_fma_f32 v[24:25], v[2:3], v[24:25], v[4:5]
	v_pk_fma_f32 v[26:27], v[10:11], v[18:19], v[26:27]
	v_pk_fma_f32 v[18:19], v[6:7], v[18:19], v[24:25]
	v_mul_f32_e32 v0, 0xbfb8aa3b, v26
	v_exp_f32_e32 v0, v0
	v_pk_fma_f32 v[18:19], v[8:9], v[16:17], v[18:19]
	v_add_f32_e32 v0, 1.0, v0
	v_rcp_f32_e32 v28, v0
	v_mul_f32_e32 v0, 0xbfb8aa3b, v27
	v_exp_f32_e32 v0, v0
	v_pk_fma_f32 v[18:19], v[10:11], v[14:15], v[18:19]
	v_add_f32_e32 v0, 1.0, v0
	v_rcp_f32_e32 v29, v0
	v_mul_f32_e32 v0, 0xbfb8aa3b, v18
	v_exp_f32_e32 v0, v0
	v_pk_mul_f32 v[26:27], v[26:27], v[28:29]
	v_add_f32_e32 v0, 1.0, v0
	v_rcp_f32_e32 v24, v0
	v_mul_f32_e32 v0, 0xbfb8aa3b, v19
	v_exp_f32_e32 v0, v0
	s_nop 0
	v_add_f32_e32 v0, 1.0, v0
	v_rcp_f32_e32 v25, v0
	s_nop 0
	v_pk_mul_f32 v[24:25], v[18:19], v[24:25]
	v_cvt_pk_bf16_f32 v18, v20, v21
	v_cvt_pk_bf16_f32 v19, v22, v23
	v_cvt_pk_bf16_f32 v20, v26, v27
	v_cvt_pk_bf16_f32 v21, v24, v25
	global_store_dwordx4 v[12:13], v[18:21], off
	v_lshl_add_u64 v[12:13], v[12:13], 0, 32
	s_cbranch_scc1 .LBB0_735
